# grid barrier: L1 invalidate issued before the spin / behind the arrival atomic instead of after the release
# speedup vs baseline: 1.0086x; 1.0086x over previous
; __device__ __forceinline__ unsigned xb_ld(unsigned* p)              { return __hip_atomic_load(p, __ATOMIC_RELAXED, __HIP_MEMORY_SCOPE_AGENT); }
; #define XB_SPIN(cond, bar) do { unsigned _sp = 0; while (cond) { __builtin_amdgcn_s_sleep(1); \
;     if ((++_sp & 255u) == 0u) { if (xb_ld(&(bar)[XB_TMO])) break; if (_sp > XB_SPIN_CAP) { atomicAdd(&(bar)[XB_TMO], 1u); break; } } } } while (0)
; __device__ __forceinline__ void xcd_barrier_thread0(const XcdBarrier& b) {
;     ...
;         } else {
;             XB_SPIN(xb_ld(&bar[XB_XGEN(b.x)]) == gen, bar);
;             __builtin_amdgcn_fence(__ATOMIC_ACQUIRE, "agent");
;             asm volatile("s_waitcnt vmcnt(0)" ::: "memory");
;         }
.LBB0_14:
	s_or_b64 exec, exec, s[0:1]
	s_waitcnt vmcnt(0)
	s_waitcnt vmcnt(0)

; __device__ __forceinline__ unsigned xb_ld(unsigned* p)              { return __hip_atomic_load(p, __ATOMIC_RELAXED, __HIP_MEMORY_SCOPE_AGENT); }
; __device__ __forceinline__ unsigned xb_add(unsigned* p, unsigned v) { return __hip_atomic_fetch_add(p, v, __ATOMIC_RELAXED, __HIP_MEMORY_SCOPE_AGENT); }
; #define XB_SPIN(cond, bar) do { unsigned _sp = 0; while (cond) { __builtin_amdgcn_s_sleep(1); \
;     if ((++_sp & 255u) == 0u) { if (xb_ld(&(bar)[XB_TMO])) break; if (_sp > XB_SPIN_CAP) { atomicAdd(&(bar)[XB_TMO], 1u); break; } } } } while (0)
; __device__ __forceinline__ void xcd_barrier_thread0(const XcdBarrier& b) {
;     ...
;         const unsigned old = xb_add(&bar[XB_XSUB(b.x)], 1u);
;         const unsigned gen = old / nloc;
;         if (old + 1u == (gen + 1u) * nloc) {
;             __builtin_amdgcn_fence(__ATOMIC_RELEASE, "agent");
;             asm volatile("s_waitcnt vmcnt(0)" ::: "memory");
;             const unsigned og = xb_add(&bar[XB_TOP], 1u);
;             const unsigned tg = og / nx;
;             if (og + 1u == (tg + 1u) * nx) xb_add(&bar[XB_TOPGEN], 1u);
;             else XB_SPIN(xb_ld(&bar[XB_TOPGEN]) == tg, bar);
;             __builtin_amdgcn_fence(__ATOMIC_ACQUIRE, "agent");
;             xb_add(&bar[XB_XGEN(b.x)], 1u);
;             asm volatile("s_waitcnt vmcnt(0)" ::: "memory");
;         } else {
;             XB_SPIN(xb_ld(&bar[XB_XGEN(b.x)]) == gen, bar);
.LBB0_501:
	s_or_b64 exec, exec, s[0:1]
	v_cvt_f32_u32_e32 v9, v7
	s_waitcnt vmcnt(0)
	v_readfirstlane_b32 s0, v8
	v_sub_u32_e32 v8, 0, v7
	v_rcp_iflag_f32_e32 v9, v9
	v_add_u32_e32 v10, s0, v5
	v_mul_f32_e32 v9, 0x4f7ffffe, v9
	v_cvt_u32_f32_e32 v9, v9
	v_mul_lo_u32 v5, v8, v9
	v_mul_hi_u32 v5, v9, v5
	v_add_u32_e32 v5, v9, v5
	v_mul_hi_u32 v5, v10, v5
	v_mul_lo_u32 v8, v5, v7
	v_sub_u32_e32 v8, v10, v8
	v_add_u32_e32 v9, 1, v5
	v_cmp_ge_u32_e32 vcc, v8, v7
	s_nop 1
	v_cndmask_b32_e32 v5, v5, v9, vcc
	v_sub_u32_e32 v9, v8, v7
	v_cndmask_b32_e32 v8, v8, v9, vcc
	v_add_u32_e32 v9, 1, v5
	v_cmp_ge_u32_e32 vcc, v8, v7
	v_add_u32_e32 v8, 1, v10
	s_nop 0
	v_cndmask_b32_e32 v5, v5, v9, vcc
	v_mul_lo_u32 v9, v7, v5
	v_add_u32_e32 v7, v9, v7
	v_cmp_ne_u32_e32 vcc, v8, v7
	s_and_saveexec_b64 s[0:1], vcc
	s_xor_b64 s[0:1], exec, s[0:1]
	s_cbranch_execz .LBB0_515
	v_readlane_b32 s6, v253, 10
	v_readlane_b32 s7, v253, 11
	s_waitcnt lgkmcnt(0)
	s_nop 3
	buffer_inv sc1
	global_load_dword v4, v3, s[6:7] sc1
	s_waitcnt vmcnt(0)
	v_cmp_eq_u32_e32 vcc, v4, v5
	s_and_saveexec_b64 s[6:7], vcc
	s_cbranch_execz .LBB0_514
	s_mov_b32 s15, 1
	s_mov_b64 s[8:9], 0
	s_branch .LBB0_505

; __device__ __forceinline__ unsigned xb_ld(unsigned* p)              { return __hip_atomic_load(p, __ATOMIC_RELAXED, __HIP_MEMORY_SCOPE_AGENT); }
; #define XB_SPIN(cond, bar) do { unsigned _sp = 0; while (cond) { __builtin_amdgcn_s_sleep(1); \
;     if ((++_sp & 255u) == 0u) { if (xb_ld(&(bar)[XB_TMO])) break; if (_sp > XB_SPIN_CAP) { atomicAdd(&(bar)[XB_TMO], 1u); break; } } } } while (0)
; __device__ __forceinline__ void xcd_barrier_thread0(const XcdBarrier& b) {
;     ...
;             XB_SPIN(xb_ld(&bar[XB_XGEN(b.x)]) == gen, bar);
;             __builtin_amdgcn_fence(__ATOMIC_ACQUIRE, "agent");
;             asm volatile("s_waitcnt vmcnt(0)" ::: "memory");
;         }
.LBB0_514:
	s_or_b64 exec, exec, s[6:7]
	s_waitcnt vmcnt(0)
	s_waitcnt vmcnt(0)

; __device__ __forceinline__ unsigned xb_ld(unsigned* p)              { return __hip_atomic_load(p, __ATOMIC_RELAXED, __HIP_MEMORY_SCOPE_AGENT); }
; __device__ __forceinline__ unsigned xb_add(unsigned* p, unsigned v) { return __hip_atomic_fetch_add(p, v, __ATOMIC_RELAXED, __HIP_MEMORY_SCOPE_AGENT); }
; #define XB_SPIN(cond, bar) do { unsigned _sp = 0; while (cond) { __builtin_amdgcn_s_sleep(1); \
;     if ((++_sp & 255u) == 0u) { if (xb_ld(&(bar)[XB_TMO])) break; if (_sp > XB_SPIN_CAP) { atomicAdd(&(bar)[XB_TMO], 1u); break; } } } } while (0)
; __device__ __forceinline__ void xcd_barrier_thread0(const XcdBarrier& b) {
;     ...
;             const unsigned og = xb_add(&bar[XB_TOP], 1u);
;             const unsigned tg = og / nx;
;             if (og + 1u == (tg + 1u) * nx) xb_add(&bar[XB_TOPGEN], 1u);
;             else XB_SPIN(xb_ld(&bar[XB_TOPGEN]) == tg, bar);
;             __builtin_amdgcn_fence(__ATOMIC_ACQUIRE, "agent");
.LBB0_518:
	s_or_b64 exec, exec, s[8:9]
	buffer_inv sc1
	s_waitcnt vmcnt(1)
	v_readfirstlane_b32 s6, v7
	v_cvt_f32_u32_e32 v7, v4
	v_sub_u32_e32 v8, 0, v4
	v_add_u32_e32 v5, s6, v5
	v_readlane_b32 s6, v253, 14
	v_rcp_iflag_f32_e32 v7, v7
	v_readlane_b32 s7, v253, 15
	s_mov_b64 s[8:9], -1
	v_mul_f32_e32 v7, 0x4f7ffffe, v7
	v_cvt_u32_f32_e32 v7, v7
	v_mul_lo_u32 v8, v8, v7
	v_mul_hi_u32 v8, v7, v8
	v_add_u32_e32 v7, v7, v8
	v_mul_hi_u32 v7, v5, v7
	v_mul_lo_u32 v8, v7, v4
	v_sub_u32_e32 v8, v5, v8
	v_cmp_ge_u32_e32 vcc, v8, v4
	v_add_u32_e32 v9, 1, v7
	v_add_u32_e32 v5, 1, v5
	v_cndmask_b32_e32 v7, v7, v9, vcc
	v_sub_u32_e32 v9, v8, v4
	v_cndmask_b32_e32 v8, v8, v9, vcc
	v_cmp_ge_u32_e32 vcc, v8, v4
	v_add_u32_e32 v8, 1, v7
	s_nop 0
	v_cndmask_b32_e32 v7, v7, v8, vcc
	v_mul_lo_u32 v8, v4, v7
	v_add_u32_e32 v4, v8, v4
	v_cmp_ne_u32_e32 vcc, v5, v4
	v_mov_b64_e32 v[4:5], s[6:7]
	s_and_saveexec_b64 s[6:7], vcc
	s_cbranch_execz .LBB0_530
	v_readlane_b32 s8, v253, 14
	v_readlane_b32 s9, v253, 15
	s_mov_b64 s[12:13], 0
	s_nop 3
	global_load_dword v4, v3, s[8:9] sc1
	s_waitcnt vmcnt(0)
	v_cmp_eq_u32_e32 vcc, v4, v7
	s_and_saveexec_b64 s[8:9], vcc
	s_cbranch_execz .LBB0_529
	s_mov_b32 s15, 1
	s_branch .LBB0_522

; __device__ __forceinline__ unsigned xb_ld(unsigned* p)              { return __hip_atomic_load(p, __ATOMIC_RELAXED, __HIP_MEMORY_SCOPE_AGENT); }
; __device__ __forceinline__ unsigned xb_add(unsigned* p, unsigned v) { return __hip_atomic_fetch_add(p, v, __ATOMIC_RELAXED, __HIP_MEMORY_SCOPE_AGENT); }
; #define XB_SPIN(cond, bar) do { unsigned _sp = 0; while (cond) { __builtin_amdgcn_s_sleep(1); \
;     if ((++_sp & 255u) == 0u) { if (xb_ld(&(bar)[XB_TMO])) break; if (_sp > XB_SPIN_CAP) { atomicAdd(&(bar)[XB_TMO], 1u); break; } } } } while (0)
; __device__ __forceinline__ void xcd_barrier_thread0(const XcdBarrier& b) {
;     ...
;             else XB_SPIN(xb_ld(&bar[XB_TOPGEN]) == tg, bar);
;             __builtin_amdgcn_fence(__ATOMIC_ACQUIRE, "agent");
;             xb_add(&bar[XB_XGEN(b.x)], 1u);
;             asm volatile("s_waitcnt vmcnt(0)" ::: "memory");
.LBB0_532:
	s_or_b64 exec, exec, s[6:7]
	s_mov_b64 s[6:7], exec
	v_mbcnt_lo_u32_b32 v4, s6, 0
	v_mbcnt_hi_u32_b32 v4, s7, v4
	v_cmp_eq_u32_e32 vcc, 0, v4
	s_waitcnt vmcnt(0)
	s_and_saveexec_b64 s[8:9], vcc
	s_cbranch_execz .LBB0_534
	s_bcnt1_i32_b64 s6, s[6:7]
	v_mov_b32_e32 v4, s6
	v_readlane_b32 s6, v253, 10
	v_readlane_b32 s7, v253, 11
	s_nop 4
	global_atomic_add v3, v4, s[6:7]

; __device__ __forceinline__ unsigned xb_ld(unsigned* p)              { return __hip_atomic_load(p, __ATOMIC_RELAXED, __HIP_MEMORY_SCOPE_AGENT); }
; __device__ __forceinline__ unsigned xb_add(unsigned* p, unsigned v) { return __hip_atomic_fetch_add(p, v, __ATOMIC_RELAXED, __HIP_MEMORY_SCOPE_AGENT); }
; #define XB_SPIN(cond, bar) do { unsigned _sp = 0; while (cond) { __builtin_amdgcn_s_sleep(1); \
;     if ((++_sp & 255u) == 0u) { if (xb_ld(&(bar)[XB_TMO])) break; if (_sp > XB_SPIN_CAP) { atomicAdd(&(bar)[XB_TMO], 1u); break; } } } } while (0)
; __device__ __forceinline__ void xcc_barrier_thread0(const XcdBarrier& b) {
;     ...
;     const unsigned nloc = b.st[0];
;     const unsigned old = xb_add(&bar[XL_SUB(b.x)], 1u);
;     const unsigned gen = old / nloc;
;     if (old + 1u == (gen + 1u) * nloc) xb_add(&bar[XL_GEN(b.x)], 1u);
;     else XB_SPIN(xb_ld(&bar[XL_GEN(b.x)]) == gen, bar);
;     __builtin_amdgcn_fence(__ATOMIC_ACQUIRE, "agent");
;     asm volatile("s_waitcnt vmcnt(0)" ::: "memory");
.LBB0_539:
	s_or_b64 exec, exec, s[0:1]
	buffer_inv sc1
	s_waitcnt vmcnt(1)
	v_readfirstlane_b32 s0, v5
	v_cvt_f32_u32_e32 v5, v6
	v_sub_u32_e32 v7, 0, v6
	v_add_u32_e32 v4, s0, v4
	v_readlane_b32 s0, v253, 18
	v_rcp_iflag_f32_e32 v5, v5
	v_readlane_b32 s1, v253, 19
	s_mov_b64 s[6:7], -1
	v_mul_f32_e32 v5, 0x4f7ffffe, v5
	v_cvt_u32_f32_e32 v5, v5
	v_mul_lo_u32 v7, v7, v5
	v_mul_hi_u32 v7, v5, v7
	v_add_u32_e32 v5, v5, v7
	v_mul_hi_u32 v5, v4, v5
	v_mul_lo_u32 v7, v5, v6
	v_sub_u32_e32 v7, v4, v7
	v_cmp_ge_u32_e32 vcc, v7, v6
	v_add_u32_e32 v8, 1, v5
	v_add_u32_e32 v4, 1, v4
	v_cndmask_b32_e32 v5, v5, v8, vcc
	v_sub_u32_e32 v8, v7, v6
	v_cndmask_b32_e32 v7, v7, v8, vcc
	v_cmp_ge_u32_e32 vcc, v7, v6
	v_add_u32_e32 v7, 1, v5
	s_nop 0
	v_cndmask_b32_e32 v7, v5, v7, vcc
	v_mul_lo_u32 v5, v6, v7
	v_add_u32_e32 v5, v5, v6
	v_cmp_ne_u32_e32 vcc, v4, v5
	v_mov_b64_e32 v[4:5], s[0:1]
	s_and_saveexec_b64 s[0:1], vcc
	s_cbranch_execz .LBB0_551
	v_readlane_b32 s6, v253, 18
	v_readlane_b32 s7, v253, 19
	s_mov_b64 s[8:9], 0
	s_nop 3
	global_load_dword v4, v3, s[6:7] sc1
	s_waitcnt vmcnt(0)
	v_cmp_eq_u32_e32 vcc, v4, v7
	s_and_saveexec_b64 s[6:7], vcc
	s_cbranch_execz .LBB0_550
	s_mov_b32 s15, 1
	s_branch .LBB0_543

; __device__ __forceinline__ unsigned xb_ld(unsigned* p)              { return __hip_atomic_load(p, __ATOMIC_RELAXED, __HIP_MEMORY_SCOPE_AGENT); }
; __device__ __forceinline__ unsigned xb_add(unsigned* p, unsigned v) { return __hip_atomic_fetch_add(p, v, __ATOMIC_RELAXED, __HIP_MEMORY_SCOPE_AGENT); }
; #define XB_SPIN(cond, bar) do { unsigned _sp = 0; while (cond) { __builtin_amdgcn_s_sleep(1); \
;     if ((++_sp & 255u) == 0u) { if (xb_ld(&(bar)[XB_TMO])) break; if (_sp > XB_SPIN_CAP) { atomicAdd(&(bar)[XB_TMO], 1u); break; } } } } while (0)
; __device__ __forceinline__ void xcd_barrier_thread0(const XcdBarrier& b) {
;     ...
;         const unsigned old = xb_add(&bar[XB_XSUB(b.x)], 1u);
;         const unsigned gen = old / nloc;
;         if (old + 1u == (gen + 1u) * nloc) {
;             __builtin_amdgcn_fence(__ATOMIC_RELEASE, "agent");
;             asm volatile("s_waitcnt vmcnt(0)" ::: "memory");
;             const unsigned og = xb_add(&bar[XB_TOP], 1u);
;             const unsigned tg = og / nx;
;             if (og + 1u == (tg + 1u) * nx) xb_add(&bar[XB_TOPGEN], 1u);
;             else XB_SPIN(xb_ld(&bar[XB_TOPGEN]) == tg, bar);
;             __builtin_amdgcn_fence(__ATOMIC_ACQUIRE, "agent");
;             xb_add(&bar[XB_XGEN(b.x)], 1u);
;             asm volatile("s_waitcnt vmcnt(0)" ::: "memory");
;         } else {
;             XB_SPIN(xb_ld(&bar[XB_XGEN(b.x)]) == gen, bar);
.LBB0_721:
	s_or_b64 exec, exec, s[0:1]
	v_cvt_f32_u32_e32 v7, v5
	s_waitcnt vmcnt(0)
	v_readfirstlane_b32 s0, v6
	v_sub_u32_e32 v6, 0, v5
	v_rcp_iflag_f32_e32 v7, v7
	v_add_u32_e32 v8, s0, v2
	v_mul_f32_e32 v7, 0x4f7ffffe, v7
	v_cvt_u32_f32_e32 v7, v7
	v_mul_lo_u32 v2, v6, v7
	v_mul_hi_u32 v2, v7, v2
	v_add_u32_e32 v2, v7, v2
	v_mul_hi_u32 v2, v8, v2
	v_mul_lo_u32 v6, v2, v5
	v_sub_u32_e32 v6, v8, v6
	v_add_u32_e32 v7, 1, v2
	v_cmp_ge_u32_e32 vcc, v6, v5
	s_nop 1
	v_cndmask_b32_e32 v2, v2, v7, vcc
	v_sub_u32_e32 v7, v6, v5
	v_cndmask_b32_e32 v6, v6, v7, vcc
	v_add_u32_e32 v7, 1, v2
	v_cmp_ge_u32_e32 vcc, v6, v5
	v_add_u32_e32 v6, 1, v8
	s_nop 0
	v_cndmask_b32_e32 v2, v2, v7, vcc
	v_mul_lo_u32 v7, v5, v2
	v_add_u32_e32 v5, v7, v5
	v_cmp_ne_u32_e32 vcc, v6, v5
	s_and_saveexec_b64 s[0:1], vcc
	s_xor_b64 s[0:1], exec, s[0:1]
	s_cbranch_execz .LBB0_735
	v_readlane_b32 s8, v253, 10
	v_readlane_b32 s9, v253, 11
	s_waitcnt lgkmcnt(0)
	s_nop 3
	buffer_inv sc1
	global_load_dword v4, v3, s[8:9] sc1
	s_waitcnt vmcnt(0)
	v_cmp_eq_u32_e32 vcc, v4, v2
	s_and_saveexec_b64 s[8:9], vcc
	s_cbranch_execz .LBB0_734
	s_mov_b32 s15, 1
	s_mov_b64 s[12:13], 0
	s_branch .LBB0_725

; __device__ __forceinline__ unsigned xb_ld(unsigned* p)              { return __hip_atomic_load(p, __ATOMIC_RELAXED, __HIP_MEMORY_SCOPE_AGENT); }
; #define XB_SPIN(cond, bar) do { unsigned _sp = 0; while (cond) { __builtin_amdgcn_s_sleep(1); \
;     if ((++_sp & 255u) == 0u) { if (xb_ld(&(bar)[XB_TMO])) break; if (_sp > XB_SPIN_CAP) { atomicAdd(&(bar)[XB_TMO], 1u); break; } } } } while (0)
; __device__ __forceinline__ void xcd_barrier_thread0(const XcdBarrier& b) {
;     ...
;             XB_SPIN(xb_ld(&bar[XB_XGEN(b.x)]) == gen, bar);
;             __builtin_amdgcn_fence(__ATOMIC_ACQUIRE, "agent");
;             asm volatile("s_waitcnt vmcnt(0)" ::: "memory");
;         }
.LBB0_734:
	s_or_b64 exec, exec, s[8:9]
	s_waitcnt vmcnt(0)
	s_waitcnt vmcnt(0)

; __device__ __forceinline__ unsigned xb_ld(unsigned* p)              { return __hip_atomic_load(p, __ATOMIC_RELAXED, __HIP_MEMORY_SCOPE_AGENT); }
; __device__ __forceinline__ unsigned xb_add(unsigned* p, unsigned v) { return __hip_atomic_fetch_add(p, v, __ATOMIC_RELAXED, __HIP_MEMORY_SCOPE_AGENT); }
; #define XB_SPIN(cond, bar) do { unsigned _sp = 0; while (cond) { __builtin_amdgcn_s_sleep(1); \
;     if ((++_sp & 255u) == 0u) { if (xb_ld(&(bar)[XB_TMO])) break; if (_sp > XB_SPIN_CAP) { atomicAdd(&(bar)[XB_TMO], 1u); break; } } } } while (0)
; __device__ __forceinline__ void xcd_barrier_thread0(const XcdBarrier& b) {
;     ...
;             const unsigned og = xb_add(&bar[XB_TOP], 1u);
;             const unsigned tg = og / nx;
;             if (og + 1u == (tg + 1u) * nx) xb_add(&bar[XB_TOPGEN], 1u);
;             else XB_SPIN(xb_ld(&bar[XB_TOPGEN]) == tg, bar);
;             __builtin_amdgcn_fence(__ATOMIC_ACQUIRE, "agent");
.LBB0_738:
	s_or_b64 exec, exec, s[8:9]
	buffer_inv sc1
	s_waitcnt vmcnt(1)
	v_readfirstlane_b32 s0, v5
	v_sub_u32_e32 v6, 0, v4
	s_mov_b64 s[8:9], -1
	v_add_u32_e32 v5, s0, v2
	v_cvt_f32_u32_e32 v2, v4
	v_readlane_b32 s0, v253, 14
	v_readlane_b32 s1, v253, 15
	v_rcp_iflag_f32_e32 v2, v2
	s_nop 0
	v_mul_f32_e32 v2, 0x4f7ffffe, v2
	v_cvt_u32_f32_e32 v2, v2
	v_mul_lo_u32 v6, v6, v2
	v_mul_hi_u32 v6, v2, v6
	v_add_u32_e32 v2, v2, v6
	v_mul_hi_u32 v2, v5, v2
	v_mul_lo_u32 v6, v2, v4
	v_sub_u32_e32 v6, v5, v6
	v_cmp_ge_u32_e32 vcc, v6, v4
	v_add_u32_e32 v7, 1, v2
	v_add_u32_e32 v5, 1, v5
	v_cndmask_b32_e32 v2, v2, v7, vcc
	v_sub_u32_e32 v7, v6, v4
	v_cndmask_b32_e32 v6, v6, v7, vcc
	v_cmp_ge_u32_e32 vcc, v6, v4
	v_add_u32_e32 v6, 1, v2
	s_nop 0
	v_cndmask_b32_e32 v2, v2, v6, vcc
	v_mul_lo_u32 v6, v4, v2
	v_add_u32_e32 v4, v6, v4
	v_cmp_ne_u32_e32 vcc, v5, v4
	v_mov_b64_e32 v[4:5], s[0:1]
	s_and_saveexec_b64 s[0:1], vcc
	s_cbranch_execz .LBB0_750
	v_readlane_b32 s8, v253, 14
	v_readlane_b32 s9, v253, 15
	s_mov_b64 s[12:13], 0
	s_nop 3
	global_load_dword v4, v3, s[8:9] sc1
	s_waitcnt vmcnt(0)
	v_cmp_eq_u32_e32 vcc, v4, v2
	s_and_saveexec_b64 s[8:9], vcc
	s_cbranch_execz .LBB0_749
	s_mov_b32 s15, 1
	s_branch .LBB0_742

; __device__ __forceinline__ unsigned xb_ld(unsigned* p)              { return __hip_atomic_load(p, __ATOMIC_RELAXED, __HIP_MEMORY_SCOPE_AGENT); }
; __device__ __forceinline__ unsigned xb_add(unsigned* p, unsigned v) { return __hip_atomic_fetch_add(p, v, __ATOMIC_RELAXED, __HIP_MEMORY_SCOPE_AGENT); }
; #define XB_SPIN(cond, bar) do { unsigned _sp = 0; while (cond) { __builtin_amdgcn_s_sleep(1); \
;     if ((++_sp & 255u) == 0u) { if (xb_ld(&(bar)[XB_TMO])) break; if (_sp > XB_SPIN_CAP) { atomicAdd(&(bar)[XB_TMO], 1u); break; } } } } while (0)
; __device__ __forceinline__ void xcd_barrier_thread0(const XcdBarrier& b) {
;     ...
;             else XB_SPIN(xb_ld(&bar[XB_TOPGEN]) == tg, bar);
;             __builtin_amdgcn_fence(__ATOMIC_ACQUIRE, "agent");
;             xb_add(&bar[XB_XGEN(b.x)], 1u);
;             asm volatile("s_waitcnt vmcnt(0)" ::: "memory");
.LBB0_752:
	s_or_b64 exec, exec, s[0:1]
	s_mov_b64 s[0:1], exec
	v_mbcnt_lo_u32_b32 v2, s0, 0
	v_mbcnt_hi_u32_b32 v2, s1, v2
	v_cmp_eq_u32_e32 vcc, 0, v2
	s_waitcnt vmcnt(0)
	s_and_saveexec_b64 s[8:9], vcc
	s_cbranch_execz .LBB0_754
	s_bcnt1_i32_b64 s0, s[0:1]
	v_mov_b32_e32 v2, s0
	v_readlane_b32 s0, v253, 10
	v_readlane_b32 s1, v253, 11
	s_nop 4
	global_atomic_add v3, v2, s[0:1]

; __device__ __forceinline__ unsigned xb_ld(unsigned* p)              { return __hip_atomic_load(p, __ATOMIC_RELAXED, __HIP_MEMORY_SCOPE_AGENT); }
; __device__ __forceinline__ unsigned xb_add(unsigned* p, unsigned v) { return __hip_atomic_fetch_add(p, v, __ATOMIC_RELAXED, __HIP_MEMORY_SCOPE_AGENT); }
; #define XB_SPIN(cond, bar) do { unsigned _sp = 0; while (cond) { __builtin_amdgcn_s_sleep(1); \
;     if ((++_sp & 255u) == 0u) { if (xb_ld(&(bar)[XB_TMO])) break; if (_sp > XB_SPIN_CAP) { atomicAdd(&(bar)[XB_TMO], 1u); break; } } } } while (0)
; __device__ __forceinline__ void xcd_barrier_thread0(const XcdBarrier& b) {
;     ...
;         const unsigned old = xb_add(&bar[XB_XSUB(b.x)], 1u);
;         const unsigned gen = old / nloc;
;         if (old + 1u == (gen + 1u) * nloc) {
;             __builtin_amdgcn_fence(__ATOMIC_RELEASE, "agent");
;             asm volatile("s_waitcnt vmcnt(0)" ::: "memory");
;             const unsigned og = xb_add(&bar[XB_TOP], 1u);
;             const unsigned tg = og / nx;
;             if (og + 1u == (tg + 1u) * nx) xb_add(&bar[XB_TOPGEN], 1u);
;             else XB_SPIN(xb_ld(&bar[XB_TOPGEN]) == tg, bar);
;             __builtin_amdgcn_fence(__ATOMIC_ACQUIRE, "agent");
;             xb_add(&bar[XB_XGEN(b.x)], 1u);
;             asm volatile("s_waitcnt vmcnt(0)" ::: "memory");
;         } else {
;             XB_SPIN(xb_ld(&bar[XB_XGEN(b.x)]) == gen, bar);
.LBB0_1036:
	s_or_b64 exec, exec, s[0:1]
	v_cvt_f32_u32_e32 v8, v6
	s_waitcnt vmcnt(0)
	v_readfirstlane_b32 s0, v7
	v_sub_u32_e32 v7, 0, v6
	v_rcp_iflag_f32_e32 v8, v8
	v_add_u32_e32 v9, s0, v5
	v_mul_f32_e32 v8, 0x4f7ffffe, v8
	v_cvt_u32_f32_e32 v8, v8
	v_mul_lo_u32 v5, v7, v8
	v_mul_hi_u32 v5, v8, v5
	v_add_u32_e32 v5, v8, v5
	v_mul_hi_u32 v5, v9, v5
	v_mul_lo_u32 v7, v5, v6
	v_sub_u32_e32 v7, v9, v7
	v_add_u32_e32 v8, 1, v5
	v_cmp_ge_u32_e32 vcc, v7, v6
	s_nop 1
	v_cndmask_b32_e32 v5, v5, v8, vcc
	v_sub_u32_e32 v8, v7, v6
	v_cndmask_b32_e32 v7, v7, v8, vcc
	v_add_u32_e32 v8, 1, v5
	v_cmp_ge_u32_e32 vcc, v7, v6
	v_add_u32_e32 v7, 1, v9
	s_nop 0
	v_cndmask_b32_e32 v5, v5, v8, vcc
	v_mul_lo_u32 v8, v6, v5
	v_add_u32_e32 v6, v8, v6
	v_cmp_ne_u32_e32 vcc, v7, v6
	s_and_saveexec_b64 s[0:1], vcc
	s_xor_b64 s[0:1], exec, s[0:1]
	s_cbranch_execz .LBB0_1050
	v_readlane_b32 s2, v253, 10
	v_readlane_b32 s3, v253, 11
	s_waitcnt lgkmcnt(0)
	s_nop 3
	buffer_inv sc1
	global_load_dword v4, v3, s[2:3] sc1
	s_waitcnt vmcnt(0)
	v_cmp_eq_u32_e32 vcc, v4, v5
	s_and_saveexec_b64 s[2:3], vcc
	s_cbranch_execz .LBB0_1049
	s_mov_b32 s15, 1
	s_mov_b64 s[8:9], 0
	s_branch .LBB0_1040

; __device__ __forceinline__ unsigned xb_ld(unsigned* p)              { return __hip_atomic_load(p, __ATOMIC_RELAXED, __HIP_MEMORY_SCOPE_AGENT); }
; #define XB_SPIN(cond, bar) do { unsigned _sp = 0; while (cond) { __builtin_amdgcn_s_sleep(1); \
;     if ((++_sp & 255u) == 0u) { if (xb_ld(&(bar)[XB_TMO])) break; if (_sp > XB_SPIN_CAP) { atomicAdd(&(bar)[XB_TMO], 1u); break; } } } } while (0)
; __device__ __forceinline__ void xcd_barrier_thread0(const XcdBarrier& b) {
;     ...
;             XB_SPIN(xb_ld(&bar[XB_XGEN(b.x)]) == gen, bar);
;             __builtin_amdgcn_fence(__ATOMIC_ACQUIRE, "agent");
;             asm volatile("s_waitcnt vmcnt(0)" ::: "memory");
;         }
.LBB0_1049:
	s_or_b64 exec, exec, s[2:3]
	s_waitcnt vmcnt(0)
	s_waitcnt vmcnt(0)

; __device__ __forceinline__ unsigned xb_ld(unsigned* p)              { return __hip_atomic_load(p, __ATOMIC_RELAXED, __HIP_MEMORY_SCOPE_AGENT); }
; __device__ __forceinline__ unsigned xb_add(unsigned* p, unsigned v) { return __hip_atomic_fetch_add(p, v, __ATOMIC_RELAXED, __HIP_MEMORY_SCOPE_AGENT); }
; #define XB_SPIN(cond, bar) do { unsigned _sp = 0; while (cond) { __builtin_amdgcn_s_sleep(1); \
;     if ((++_sp & 255u) == 0u) { if (xb_ld(&(bar)[XB_TMO])) break; if (_sp > XB_SPIN_CAP) { atomicAdd(&(bar)[XB_TMO], 1u); break; } } } } while (0)
; __device__ __forceinline__ void xcd_barrier_thread0(const XcdBarrier& b) {
;     ...
;             const unsigned og = xb_add(&bar[XB_TOP], 1u);
;             const unsigned tg = og / nx;
;             if (og + 1u == (tg + 1u) * nx) xb_add(&bar[XB_TOPGEN], 1u);
;             else XB_SPIN(xb_ld(&bar[XB_TOPGEN]) == tg, bar);
;             __builtin_amdgcn_fence(__ATOMIC_ACQUIRE, "agent");
.LBB0_1053:
	s_or_b64 exec, exec, s[8:9]
	buffer_inv sc1
	s_waitcnt vmcnt(1)
	v_readfirstlane_b32 s2, v6
	v_cvt_f32_u32_e32 v6, v4
	v_sub_u32_e32 v7, 0, v4
	v_add_u32_e32 v5, s2, v5
	v_readlane_b32 s2, v253, 14
	v_rcp_iflag_f32_e32 v6, v6
	v_readlane_b32 s3, v253, 15
	s_mov_b64 s[8:9], -1
	v_mul_f32_e32 v6, 0x4f7ffffe, v6
	v_cvt_u32_f32_e32 v6, v6
	v_mul_lo_u32 v7, v7, v6
	v_mul_hi_u32 v7, v6, v7
	v_add_u32_e32 v6, v6, v7
	v_mul_hi_u32 v6, v5, v6
	v_mul_lo_u32 v7, v6, v4
	v_sub_u32_e32 v7, v5, v7
	v_cmp_ge_u32_e32 vcc, v7, v4
	v_add_u32_e32 v8, 1, v6
	v_add_u32_e32 v5, 1, v5
	v_cndmask_b32_e32 v6, v6, v8, vcc
	v_sub_u32_e32 v8, v7, v4
	v_cndmask_b32_e32 v7, v7, v8, vcc
	v_cmp_ge_u32_e32 vcc, v7, v4
	v_add_u32_e32 v7, 1, v6
	s_nop 0
	v_cndmask_b32_e32 v6, v6, v7, vcc
	v_mul_lo_u32 v7, v4, v6
	v_add_u32_e32 v4, v7, v4
	v_cmp_ne_u32_e32 vcc, v5, v4
	v_mov_b64_e32 v[4:5], s[2:3]
	s_and_saveexec_b64 s[2:3], vcc
	s_cbranch_execz .LBB0_1065
	v_readlane_b32 s8, v253, 14
	v_readlane_b32 s9, v253, 15
	s_mov_b64 s[12:13], 0
	s_nop 3
	global_load_dword v4, v3, s[8:9] sc1
	s_waitcnt vmcnt(0)
	v_cmp_eq_u32_e32 vcc, v4, v6
	s_and_saveexec_b64 s[8:9], vcc
	s_cbranch_execz .LBB0_1064
	s_mov_b32 s15, 1
	s_branch .LBB0_1057

; __device__ __forceinline__ unsigned xb_ld(unsigned* p)              { return __hip_atomic_load(p, __ATOMIC_RELAXED, __HIP_MEMORY_SCOPE_AGENT); }
; __device__ __forceinline__ unsigned xb_add(unsigned* p, unsigned v) { return __hip_atomic_fetch_add(p, v, __ATOMIC_RELAXED, __HIP_MEMORY_SCOPE_AGENT); }
; #define XB_SPIN(cond, bar) do { unsigned _sp = 0; while (cond) { __builtin_amdgcn_s_sleep(1); \
;     if ((++_sp & 255u) == 0u) { if (xb_ld(&(bar)[XB_TMO])) break; if (_sp > XB_SPIN_CAP) { atomicAdd(&(bar)[XB_TMO], 1u); break; } } } } while (0)
; __device__ __forceinline__ void xcd_barrier_thread0(const XcdBarrier& b) {
;     ...
;             else XB_SPIN(xb_ld(&bar[XB_TOPGEN]) == tg, bar);
;             __builtin_amdgcn_fence(__ATOMIC_ACQUIRE, "agent");
;             xb_add(&bar[XB_XGEN(b.x)], 1u);
;             asm volatile("s_waitcnt vmcnt(0)" ::: "memory");
.LBB0_1067:
	s_or_b64 exec, exec, s[2:3]
	s_mov_b64 s[2:3], exec
	v_mbcnt_lo_u32_b32 v4, s2, 0
	v_mbcnt_hi_u32_b32 v4, s3, v4
	v_cmp_eq_u32_e32 vcc, 0, v4
	s_waitcnt vmcnt(0)
	s_and_saveexec_b64 s[8:9], vcc
	s_cbranch_execz .LBB0_1069
	s_bcnt1_i32_b64 s2, s[2:3]
	v_mov_b32_e32 v4, s2
	v_readlane_b32 s2, v253, 10
	v_readlane_b32 s3, v253, 11
	s_nop 4
	global_atomic_add v3, v4, s[2:3]

; __device__ __forceinline__ unsigned xb_ld(unsigned* p)              { return __hip_atomic_load(p, __ATOMIC_RELAXED, __HIP_MEMORY_SCOPE_AGENT); }
; __device__ __forceinline__ unsigned xb_add(unsigned* p, unsigned v) { return __hip_atomic_fetch_add(p, v, __ATOMIC_RELAXED, __HIP_MEMORY_SCOPE_AGENT); }
; #define XB_SPIN(cond, bar) do { unsigned _sp = 0; while (cond) { __builtin_amdgcn_s_sleep(1); \
;     if ((++_sp & 255u) == 0u) { if (xb_ld(&(bar)[XB_TMO])) break; if (_sp > XB_SPIN_CAP) { atomicAdd(&(bar)[XB_TMO], 1u); break; } } } } while (0)
; __device__ __forceinline__ void xcc_barrier_thread0(const XcdBarrier& b) {
;     ...
;     const unsigned nloc = b.st[0];
;     const unsigned old = xb_add(&bar[XL_SUB(b.x)], 1u);
;     const unsigned gen = old / nloc;
;     if (old + 1u == (gen + 1u) * nloc) xb_add(&bar[XL_GEN(b.x)], 1u);
;     else XB_SPIN(xb_ld(&bar[XL_GEN(b.x)]) == gen, bar);
;     __builtin_amdgcn_fence(__ATOMIC_ACQUIRE, "agent");
;     asm volatile("s_waitcnt vmcnt(0)" ::: "memory");
.LBB0_1074:
	s_or_b64 exec, exec, s[0:1]
	buffer_inv sc1
	s_waitcnt vmcnt(1)
	v_readfirstlane_b32 s0, v5
	v_cvt_f32_u32_e32 v5, v2
	v_sub_u32_e32 v6, 0, v2
	v_add_u32_e32 v4, s0, v4
	v_readlane_b32 s0, v253, 18
	v_rcp_iflag_f32_e32 v5, v5
	v_readlane_b32 s1, v253, 19
	s_mov_b64 s[2:3], -1
	v_mul_f32_e32 v5, 0x4f7ffffe, v5
	v_cvt_u32_f32_e32 v5, v5
	v_mul_lo_u32 v6, v6, v5
	v_mul_hi_u32 v6, v5, v6
	v_add_u32_e32 v5, v5, v6
	v_mul_hi_u32 v5, v4, v5
	v_mul_lo_u32 v6, v5, v2
	v_sub_u32_e32 v6, v4, v6
	v_cmp_ge_u32_e32 vcc, v6, v2
	v_add_u32_e32 v7, 1, v5
	v_add_u32_e32 v4, 1, v4
	v_cndmask_b32_e32 v5, v5, v7, vcc
	v_sub_u32_e32 v7, v6, v2
	v_cndmask_b32_e32 v6, v6, v7, vcc
	v_cmp_ge_u32_e32 vcc, v6, v2
	v_add_u32_e32 v6, 1, v5
	s_nop 0
	v_cndmask_b32_e32 v6, v5, v6, vcc
	v_mul_lo_u32 v5, v2, v6
	v_add_u32_e32 v2, v5, v2
	v_cmp_ne_u32_e32 vcc, v4, v2
	v_mov_b64_e32 v[4:5], s[0:1]
	s_and_saveexec_b64 s[0:1], vcc
	s_cbranch_execz .LBB0_1086
	v_readlane_b32 s2, v253, 18
	v_readlane_b32 s3, v253, 19
	s_mov_b64 s[8:9], 0
	s_nop 3
	global_load_dword v2, v3, s[2:3] sc1
	s_waitcnt vmcnt(0)
	v_cmp_eq_u32_e32 vcc, v2, v6
	s_and_saveexec_b64 s[2:3], vcc
	s_cbranch_execz .LBB0_1085
	s_mov_b32 s15, 1
	s_branch .LBB0_1078
